# GLA step1/step3: next-sub-chunk prefetch left in flight across the back edge (V^T loads retired before it), norm-gain table read from per-wave LDS; on top of full-line residual stores
# speedup vs baseline: 1.0197x; 1.0084x over previous
; __device__ __forceinline__ unsigned pk2(float lo, float hi) { return pg8::cvt_pk_bf16(lo, hi); }
; #define EX2(x) __builtin_amdgcn_exp2f(x)
; #define LDS_WAIT() asm volatile("s_waitcnt lgkmcnt(0)" ::: "memory")
; __device__ __forceinline__ void gla_state_ops(const float* ks, const float* Bs, const float* Be, int fr, int fq, bf16x4 (&ke)[2], f32x4 (&dec)[2]) {
; #pragma unroll
;     for (int kb = 0; kb < 2; ++kb) { const int kidx = kb * 16 + fr; const float be = Be[kidx]; float e[4];
; #pragma unroll
;         for (int j = 0; j < 4; ++j) e[j] = ks[(fq * 4 + j) * GS + kidx] * EX2(be - Bs[(fq * 4 + j) * GS + kidx]);
;         u32x2 w; w.x = pk2(e[0], e[1]); w.y = pk2(e[2], e[3]); ke[kb] = as_bf16x4(w);
;         const f32x4 bv = *(const f32x4*)(Be + kb * 16 + fq * 4);
;         dec[kb] = (f32x4){EX2(bv[0]), EX2(bv[1]), EX2(bv[2]), EX2(bv[3])}; }
; }
; __device__ __forceinline__ void gla_step1(ParamsK p, int l, unsigned char* smem) {
;     ...
;                 bf16x4 ke[2]; f32x4 dec[2]; gla_state_ops(ks, Bs, Be, fr, fq, ke, dec);
;                 bsum += Be[lane & 31];
; #pragma unroll
;                 for (int kb = 0; kb < 2; ++kb)
; #pragma unroll
;                     for (int db = 0; db < 4; ++db) S[kb][db] = __builtin_amdgcn_mfma_f32_16x16x16bf16_1k(ke[kb], vt[db], S[kb][db] * dec[kb], 0, 0, 0);
;                 LDS_WAIT();
.LBB0_378:
	s_mov_b32 s51, s1
	v_lshl_add_u64 v[46:47], v[46:47], 0, s[50:51]
	v_mov_b32_e32 v59, v1
	v_lshl_add_u64 v[46:47], v[46:47], 0, v[58:59]
	global_load_dwordx2 v[94:95], v[46:47], off
	v_add_u32_e32 v106, 0x1800, v118
	ds_read2_b32 v[46:47], v106 offset0:192 offset1:208
	ds_read2st64_b32 v[48:49], v119 offset0:9 offset1:18
	v_add_u32_e32 v59, 0x1000, v120
	ds_read2_b32 v[108:109], v59 offset0:144 offset1:164
	v_add_u32_e32 v102, 0x800, v120
	ds_read2_b32 v[100:101], v102 offset0:80 offset1:100
	s_waitcnt lgkmcnt(2)
	v_sub_f32_e32 v49, v46, v49
	v_exp_f32_e32 v96, v49
	s_waitcnt lgkmcnt(1)
	v_sub_f32_e32 v49, v46, v109
	v_exp_f32_e32 v97, v49
	s_waitcnt lgkmcnt(0)
	v_mov_b32_e32 v49, v101
	v_add_u32_e32 v107, 0x800, v121
	s_add_i32 s8, s8, 1
	v_pk_mul_f32 v[48:49], v[48:49], v[96:97]
	ds_read2_b32 v[96:97], v102 offset0:136 offset1:172
	ds_read2_b32 v[98:99], v59 offset0:200 offset1:236
	ds_read2_b32 v[150:151], v107 offset0:100 offset1:136
	v_cvt_pk_bf16_f32 v48, v48, v49
	s_cmp_eq_u32 s9, 0
	s_waitcnt lgkmcnt(1)
	v_sub_f32_e32 v98, v46, v98
	v_sub_f32_e32 v46, v46, v99
	v_exp_f32_e32 v99, v46
	v_sub_f32_e32 v46, v47, v108
	v_add_u32_e32 v108, 0x1000, v121
	ds_read2_b32 v[152:153], v108 offset0:164 offset1:200
	v_exp_f32_e32 v98, v98
	v_exp_f32_e32 v148, v46
	s_waitcnt lgkmcnt(1)
	v_mov_b32_e32 v101, v150
	s_waitcnt lgkmcnt(0)
	v_sub_f32_e32 v46, v47, v152
	v_exp_f32_e32 v149, v46
	v_pk_mul_f32 v[96:97], v[96:97], v[98:99]
	v_sub_f32_e32 v46, v47, v153
	v_cvt_pk_bf16_f32 v49, v96, v97
	ds_read_b128 v[96:99], v143 offset:6912
	v_pk_mul_f32 v[100:101], v[100:101], v[148:149]
	ds_read_b32 v149, v121 offset:2736
	ds_read_b32 v109, v121 offset:5040
	v_exp_f32_e32 v46, v46
	v_mov_b32_e32 v148, v151
	s_waitcnt lgkmcnt(2)
	v_exp_f32_e32 v96, v96
	v_exp_f32_e32 v97, v97
	s_waitcnt lgkmcnt(0)
	v_sub_f32_e32 v47, v47, v109
	v_exp_f32_e32 v47, v47
	v_exp_f32_e32 v98, v98
	v_exp_f32_e32 v99, v99
	ds_read_b32 v109, v114 offset:6912
	v_pk_mul_f32 v[148:149], v[148:149], v[46:47]
	v_cvt_pk_bf16_f32 v46, v100, v101
	v_cvt_pk_bf16_f32 v47, v148, v149
	ds_read_b128 v[148:151], v143 offset:6976
	v_pk_mul_f32 v[40:41], v[40:41], v[98:99]
	v_pk_mul_f32 v[38:39], v[38:39], v[96:97]
	v_pk_mul_f32 v[36:37], v[36:37], v[98:99]
	v_pk_mul_f32 v[34:35], v[34:35], v[96:97]
	s_waitcnt lgkmcnt(0)
	v_exp_f32_e32 v100, v148
	v_exp_f32_e32 v101, v149
	v_exp_f32_e32 v148, v150
	v_exp_f32_e32 v149, v151
	v_pk_mul_f32 v[32:33], v[32:33], v[98:99]
	v_pk_mul_f32 v[30:31], v[30:31], v[96:97]
	v_pk_mul_f32 v[28:29], v[28:29], v[98:99]
	v_pk_mul_f32 v[26:27], v[26:27], v[96:97]
	v_pk_mul_f32 v[24:25], v[24:25], v[148:149]
	v_pk_mul_f32 v[22:23], v[22:23], v[100:101]
	v_pk_mul_f32 v[20:21], v[20:21], v[148:149]
	v_pk_mul_f32 v[18:19], v[18:19], v[100:101]
	v_pk_mul_f32 v[16:17], v[16:17], v[148:149]
	v_pk_mul_f32 v[14:15], v[14:15], v[100:101]
	v_pk_mul_f32 v[12:13], v[12:13], v[148:149]
	v_pk_mul_f32 v[10:11], v[10:11], v[100:101]
	v_mfma_f32_16x16x16_bf16 v[38:41], v[48:49], v[92:93], v[38:41]
	s_waitcnt lgkmcnt(0)
	v_add_f32_e32 v57, v57, v109
	v_mfma_f32_16x16x16_bf16 v[34:37], v[48:49], v[90:91], v[34:37]
	v_mfma_f32_16x16x16_bf16 v[30:33], v[48:49], v[88:89], v[30:33]
	v_mfma_f32_16x16x16_bf16 v[26:29], v[48:49], v[86:87], v[26:29]
	v_mfma_f32_16x16x16_bf16 v[22:25], v[46:47], v[92:93], v[22:25]
	v_mfma_f32_16x16x16_bf16 v[18:21], v[46:47], v[90:91], v[18:21]
	v_mfma_f32_16x16x16_bf16 v[14:17], v[46:47], v[88:89], v[14:17]
	v_mfma_f32_16x16x16_bf16 v[10:13], v[46:47], v[86:87], v[10:13]
	s_cbranch_scc1 .LBB0_394

; #define LDS_WAIT() asm volatile("s_waitcnt lgkmcnt(0)" ::: "memory")
; template <bool NEEDQ>
; __device__ __forceinline__ void gla_stage16(const GlaRaw& R, float* qs, float* ks, float* Bs, float* Be, int tpos0, int dir, const float (&wg)[16], float bgk, int lane) {
;     ...
;             if (hf == 0) {
; #pragma unroll
;                 for (int i = 0; i < 8; ++i) g[i] += other;
;                 Be[k] = g[0]; }
;         }
; #pragma unroll
;         for (int i = 0; i < 8; ++i) Bs[(hf * 8 + i) * GS + k] = g[i];
;     }
;     LDS_WAIT();
; __device__ __forceinline__ void gla_step1(ParamsK p, int l, unsigned char* smem) {
;     ...
;             GlaRaw raw; { const int sc0 = dir ? NSUB - 1 : 0; gla_stage_load<false>(U, rope, rowb + sc0 * 16, tpb < 0 ? -1 : tpb + sc0 * 16, h, dir, lane, raw); }
;             for (int si = 0; si < NSUB; ++si) {
;                 const int sc = dir ? NSUB - 1 - si : si;
;                 bf16x4 vt[4];
; #pragma unroll
;                 for (int db = 0; db < 4; ++db) vt[db] = as_bf16x4(*(const u32x2*)(VTG + (size_t)(bh * 64 + db * 16 + fr) * VTW + vtb + sc * 16 + fq * 4));
;                 gla_stage16<false>(raw, qs, ks, Bs, Be, tpb, dir, wg, bgk, lane);
;                 if (si < NSUB - 1) { const int scn = dir ? NSUB - 2 - si : si + 1; gla_stage_load<false>(U, rope, rowb + scn * 16, tpb < 0 ? -1 : tpb + scn * 16, h, dir, lane, raw); }
.LBB0_390:
	s_and_saveexec_b64 s[34:35], s[52:53]
	ds_write_b32 v114, v97 offset:6912
	s_or_b64 exec, exec, s[34:35]
	s_add_i32 s9, s9, -1
	s_and_b64 s[34:35], s[24:25], exec
	s_cselect_b32 s0, s8, s9
	v_add_u32_e32 v103, 0x1000, v117
	s_lshl_b32 s0, s0, 4
	ds_write_b32 v116, v108 offset:4608
	ds_write2_b32 v103, v104, v94 offset0:164 offset1:200
	v_add_u32_e32 v104, 0x1200, v117
	s_waitcnt lgkmcnt(2)
	v_add_u32_e32 v44, s0, v144
	v_mov_b64_e32 v[42:43], s[22:23]
	ds_write2_b32 v104, v100, v46 offset0:108 offset1:144
	v_add_u32_e32 v105, 0x1400, v117
	v_mad_i64_i32 v[46:47], s[34:35], v44, s83, v[42:43]
	ds_write2_b32 v105, v98, v96 offset0:52 offset1:88
	ds_write_b32 v117, v102 offset:5616
	v_lshl_add_u64 v[42:43], s[20:21], 1, v[46:47]
	s_waitcnt lgkmcnt(0)
	v_lshl_add_u64 v[42:43], v[42:43], 0, v[0:1]
	s_waitcnt vmcnt(0)
	global_load_dwordx4 v[42:45], v[42:43], off offset:384
	s_add_i32 s0, s0, s3
	s_and_b64 s[34:35], s[26:27], exec
	s_cselect_b32 s0, -1, s0
	s_cmp_lt_i32 s0, 0
	s_cbranch_scc1 .LBB0_378
	v_add_u32_e32 v2, s0, v112
	v_mov_b32_e32 v3, v1
	v_lshlrev_b64 v[2:3], 7, v[2:3]
	v_lshl_add_u64 v[6:7], v[52:53], 0, v[2:3]
	global_load_dwordx4 v[2:5], v[6:7], off
	s_nop 0
	global_load_dwordx4 v[6:9], v[6:7], off offset:64
	s_branch .LBB0_378

; __device__ __forceinline__ int otid() { int t = threadIdx.x; asm volatile("" : "+v"(t)); return t; }
; #define IN(i) asglobal(p->in[i])
; #define WSP asglobal(p->ws)
; __device__ __forceinline__ void gla_step3(ParamsK p, int l, unsigned char* smem) {
;     const int tid = otid(), lane = tid & 63, wave = __builtin_amdgcn_readfirstlane(tid >> 6), fr = lane & 15, fq = lane >> 4;
;     float* qs = (float*)(smem + wave * 16384); float* ks = qs + 16 * GS; float* Bs = ks + 16 * GS; float* Be = Bs + 16 * GS;
;     const bf16_t* U = (const bf16_t*)(WSP + WS_U); const float* rope = (const float*)(WSP + WS_ROPE); const bf16_t* VTG = (const bf16_t*)(WSP + WS_VTG);
;     const float* SL = (const float*)(WSP + WS_SL); bf16_t* OG = (bf16_t*)(WSP + WS_OG);
;     bf16_t* MIX = (bf16_t*)(WSP + WS_H);
;     const float* ngp = IN(13) + l * 64;
;     const int gw = wave * gridDim.x + blockIdx.x, NGW = gridDim.x * 8;
;     for (int task = gw; task < 48 * NCH; task += NGW) {
;         int bh, b, h, tc, rowb, vtb, tpb; gla_task(task, bh, b, h, tc, rowb, vtb, tpb);
;         for (int dir = 0; dir < 2; ++dir) {
;             const int c = dir == 0 ? tc : (tc < NCTXC ? NCTXC - 1 - tc : (NCH - 1 + NCTXC) - tc);
;             float wg[16], bgk; gla_load_gatew(p, l, h, dir, lane, wg, bgk);
.LBB0_802:
	s_or_b64 exec, exec, s[18:19]
	v_readlane_b32 s18, v250, 13
	v_readlane_b32 s19, v250, 14
	s_waitcnt lgkmcnt(0)
	v_mov_b32_e32 v2, v163
	s_barrier
	s_nop 0
	v_readfirstlane_b32 s0, v2
	s_ashr_i32 s2, s0, 6
	s_mul_i32 s0, s2, s70
	s_add_i32 s97, s0, s11
	v_readlane_b32 s10, v250, 11
	s_cmpk_lt_i32 s97, 0x630
	v_readlane_b32 s11, v250, 12
	s_cbranch_scc0 .LBB0_839
	s_load_dwordx2 s[6:7], s[18:19], 0xc0
	s_load_dwordx2 s[8:9], s[18:19], 0x68
	v_readlane_b32 s10, v250, 19
	v_bfe_u32 v180, v2, 2, 4
	v_mul_u32_u24_e32 v11, 36, v180
	s_waitcnt lgkmcnt(0)
	s_add_u32 s72, s6, 0xf1d8000
	s_addc_u32 s73, s7, 0
	s_add_u32 s4, s6, 0x301d8000
	s_addc_u32 s5, s7, 0
	s_lshl_b32 s0, s10, 6
	s_lshl_b64 s[20:21], s[0:1], 2
	s_add_u32 s8, s8, s20
	s_addc_u32 s9, s9, s21
	s_lshl_b32 s0, s2, 14
	v_lshlrev_b32_e32 v12, 5, v2
	s_add_i32 s0, s0, 16
	v_and_b32_e32 v4, 31, v2
	v_lshlrev_b32_e32 v11, 2, v11
	v_and_b32_e32 v12, 0x60, v12
	v_and_b32_e32 v3, 63, v2
	v_bfe_u32 v5, v2, 4, 2
	v_add3_u32 v181, s0, v11, v12
	v_lshlrev_b32_e32 v11, 2, v4
	v_bfe_u32 v12, v2, 5, 1
	v_lshlrev_b32_e32 v0, 3, v5
	v_lshlrev_b32_e32 v13, 3, v3
	v_add_u32_e32 v182, s0, v11
	v_cmp_gt_u32_e64 s[38:39], 32, v3
	v_cmp_lt_u32_e64 s[40:41], 31, v3
	v_mul_u32_u24_e32 v3, 0x120, v12
	v_and_b32_e32 v10, 3, v2
	v_lshl_add_u64 v[8:9], s[6:7], 0, v[0:1]
	s_mov_b64 s[2:3], 0x2d058000
	v_lshl_add_u32 v183, v12, 8, s0
	v_lshl_add_u32 v184, v3, 2, v182
	v_mul_u32_u24_e32 v3, 0x380, v12
	v_and_b32_e32 v87, 15, v2
	v_lshlrev_b32_e32 v6, 3, v10
	v_lshl_add_u64 v[82:83], v[8:9], 0, s[2:3]
	s_mov_b64 s[2:3], 0x31afb000
	v_add3_u32 v185, v183, v3, v11
	v_lshlrev_b32_e32 v86, 2, v10
	v_lshlrev_b32_e32 v10, 4, v10
	v_mov_b32_e32 v11, v1
	v_lshl_add_u64 v[84:85], v[8:9], 0, s[2:3]
	v_lshl_add_u64 v[10:11], s[6:7], 0, v[10:11]
	s_mov_b64 s[2:3], 0x64d8000
	v_mul_u32_u24_e32 v3, 36, v87
	v_lshl_add_u64 v[88:89], v[10:11], 0, s[2:3]
	v_lshl_add_u32 v3, v3, 2, s0
	v_and_b32_e32 v2, 48, v2
	v_mul_u32_u24_e32 v10, 0x90, v5
	s_movk_i32 s2, 0xff74
	v_add_u32_e32 v186, v3, v2
	v_mad_i32_i24 v188, v87, s2, v3
	v_or_b32_e32 v3, v10, v87
	v_or_b32_e32 v11, 16, v87
	s_movk_i32 s2, 0x90
	v_lshl_add_u32 v189, v3, 2, s0
	v_mad_u32_u24 v3, v5, s2, v11
	v_lshl_add_u32 v191, v3, 2, s0
	v_mov_b32_e32 v3, v1
	v_lshl_add_u64 v[90:91], s[8:9], 0, v[2:3]
	v_add_u32_e32 v237, s0, v2
	v_and_b32_e32 v253, 63, v163
	v_lshlrev_b32_e32 v253, 2, v253
	global_load_dword v254, v253, s[8:9]
	v_add_u32_e32 v253, s0, v253
	s_waitcnt vmcnt(0)
	ds_write_b32 v253, v254 offset:8192
	s_waitcnt lgkmcnt(0)
	s_mov_b64 s[2:3], 0x6dd8000
	v_lshlrev_b32_e32 v3, 8, v5
	v_lshlrev_b32_e32 v7, 2, v5
	v_lshl_add_u64 v[92:93], v[8:9], 0, s[2:3]
	v_or_b32_e32 v5, 32, v87
	v_or_b32_e32 v9, 48, v87
	v_or_b32_e32 v15, 0x400, v3
	v_or_b32_e32 v8, v15, v87
	v_or_b32_e32 v17, 0x440, v3
	v_or_b32_e32 v19, 0x480, v3
	v_or_b32_e32 v21, 0x4c0, v3
	v_or_b32_e32 v16, v15, v11
	v_or_b32_e32 v24, v15, v5
	v_or_b32_e32 v32, v15, v9
	v_or_b32_e32 v15, 1, v7
	v_add_u32_e32 v187, s0, v2
	v_lshl_add_u32 v190, v10, 2, v188
	v_or_b32_e32 v2, v3, v87
	v_or_b32_e32 v10, v17, v87
	v_or_b32_e32 v12, v19, v87
	v_or_b32_e32 v14, v21, v87
	v_or_b32_e32 v18, v17, v11
	v_or_b32_e32 v20, v19, v11
	v_or_b32_e32 v22, v21, v11
	v_or_b32_e32 v26, v17, v5
	v_or_b32_e32 v28, v19, v5
	v_or_b32_e32 v30, v21, v5
	v_or_b32_e32 v34, v17, v9
	v_or_b32_e32 v36, v19, v9
	v_or_b32_e32 v38, v21, v9
	v_cmp_le_u32_e64 s[42:43], v7, v87
	v_cmp_ge_u32_e64 s[44:45], v7, v87
	v_cmp_lt_u32_e64 s[46:47], v7, v87
	v_cmp_ge_u32_e64 s[48:49], v15, v87
	v_or_b32_e32 v15, 2, v7
	v_or_b32_e32 v7, 3, v7
	v_or_b32_e32 v40, v3, v11
	v_or_b32_e32 v42, v3, v5
	v_or_b32_e32 v44, v3, v9
	v_cmp_le_u32_e64 s[50:51], v15, v87
	v_cmp_ge_u32_e64 s[52:53], v15, v87
	v_cmp_le_u32_e64 s[54:55], v7, v87
	v_cmp_ge_u32_e64 s[56:57], v7, v87
	v_lshl_add_u64 v[94:95], s[72:73], 0, v[0:1]
	v_lshlrev_b32_e32 v96, 2, v4
	v_lshlrev_b32_e32 v192, 2, v2
	v_lshlrev_b32_e32 v193, 2, v40
	v_lshlrev_b32_e32 v194, 2, v42
	v_lshlrev_b32_e32 v195, 2, v44
	v_lshlrev_b32_e32 v196, 2, v8
	v_lshlrev_b32_e32 v197, 2, v10
	v_lshlrev_b32_e32 v198, 2, v12
	v_lshlrev_b32_e32 v199, 2, v14
	v_lshlrev_b32_e32 v200, 2, v16
	v_lshlrev_b32_e32 v201, 2, v18
	v_lshlrev_b32_e32 v202, 2, v20
	v_lshlrev_b32_e32 v203, 2, v22
	v_lshlrev_b32_e32 v204, 2, v24
	v_lshlrev_b32_e32 v205, 2, v26
	v_lshlrev_b32_e32 v206, 2, v28
	v_lshlrev_b32_e32 v207, 2, v30
	v_lshlrev_b32_e32 v208, 2, v32
	v_lshlrev_b32_e32 v209, 2, v34
	v_lshlrev_b32_e32 v210, 2, v36
	v_lshlrev_b32_e32 v211, 2, v38
	v_lshlrev_b32_e32 v0, 1, v6
	v_add_u32_e32 v212, s0, v13
	v_readlane_b32 s11, v250, 20
	s_branch .LBB0_805

; #define LDS_WAIT() asm volatile("s_waitcnt lgkmcnt(0)" ::: "memory")
; template <bool NEEDQ>
; __device__ __forceinline__ void gla_stage16(const GlaRaw& R, float* qs, float* ks, float* Bs, float* Be, int tpos0, int dir, const float (&wg)[16], float bgk, int lane) {
;     ...
;             if (hf == 0) {
; #pragma unroll
;                 for (int i = 0; i < 8; ++i) g[i] += other;
;                 Be[k] = g[0]; }
;         }
; #pragma unroll
;         for (int i = 0; i < 8; ++i) Bs[(hf * 8 + i) * GS + k] = g[i];
;     }
;     LDS_WAIT();
; __device__ __forceinline__ void gla_step3(ParamsK p, int l, unsigned char* smem) {
;     ...
;                 if (si < NSUB - 1) { const int scn = dir ? NSUB - 2 - si : si + 1; gla_stage_load<true>(U, rope, rowb + scn * 16, tpb < 0 ? -1 : tpb + scn * 16, h, dir, lane, raw); }
.LBB0_828:
	s_and_saveexec_b64 s[34:35], s[78:79]
	ds_write_b32 v182, v77 offset:6912
	s_or_b64 exec, exec, s[34:35]
	v_add_u32_e32 v66, 0x1000, v185
	ds_write_b32 v184, v158 offset:4608
	ds_write2_b32 v66, v154, v74 offset0:164 offset1:200
	v_add_u32_e32 v66, 0x1200, v185
	ds_write2_b32 v66, v80, v70 offset0:108 offset1:144
	v_add_u32_e32 v66, 0x1400, v185
	ds_write2_b32 v66, v78, v76 offset0:52 offset1:88
	ds_write_b32 v185, v152 offset:5616
	s_waitcnt lgkmcnt(0)
	s_waitcnt vmcnt(0)
	s_cmp_eq_u32 s9, -1
	s_cbranch_scc1 .LBB0_834
	s_and_b64 s[10:11], s[20:21], exec
	s_cselect_b32 s0, s8, s9
	s_lshl_b32 s0, s0, 4
	v_add_u32_e32 v60, s0, v213
	v_mov_b64_e32 v[58:59], s[72:73]
	v_mad_i64_i32 v[66:67], s[10:11], v60, s83, v[58:59]
	v_lshl_add_u64 v[58:59], s[76:77], 1, v[66:67]
	v_lshl_add_u64 v[62:63], v[58:59], 0, v[0:1]
	global_load_dwordx4 v[58:61], v[62:63], off offset:384
	s_nop 0
	global_load_dwordx4 v[62:65], v[62:63], off
	s_add_i32 s0, s0, s3
	s_and_b64 s[10:11], s[22:23], exec
	s_cselect_b32 s0, -1, s0
	s_cmp_lt_i32 s0, 0
	s_cbranch_scc1 .LBB0_833
	v_add_u32_e32 v2, s0, v180
	v_mov_b32_e32 v3, v1
	v_lshlrev_b64 v[2:3], 7, v[2:3]
	v_lshl_add_u64 v[6:7], v[88:89], 0, v[2:3]
	global_load_dwordx4 v[2:5], v[6:7], off
	s_nop 0
	global_load_dwordx4 v[6:9], v[6:7], off offset:64

; __device__ __forceinline__ unsigned pk2(float lo, float hi) { return pg8::cvt_pk_bf16(lo, hi); }
; __device__ __forceinline__ void gla_step3(ParamsK p, int l, unsigned char* smem) {
;     ...
;                 const f32x4 ba = *(const f32x4*)(Bs + fr * GS + fq * 4), bb = *(const f32x4*)(Bs + fr * GS + 16 + fq * 4);
;                 const f32x4 qa = *(const f32x4*)(qs + fr * GS + fq * 4), qb = *(const f32x4*)(qs + fr * GS + 16 + fq * 4);
;                 const f32x4 ka = *(const f32x4*)(ks + fr * GS + fq * 4), kc = *(const f32x4*)(ks + fr * GS + 16 + fq * 4);
;                 u32x4 qw, kw;
;                 qw.x = pk2(qa[0] * EX2(ba[0]), qa[1] * EX2(ba[1])); qw.y = pk2(qa[2] * EX2(ba[2]), qa[3] * EX2(ba[3]));
;                 qw.z = pk2(qb[0] * EX2(bb[0]), qb[1] * EX2(bb[1])); qw.w = pk2(qb[2] * EX2(bb[2]), qb[3] * EX2(bb[3]));
;                 kw.x = pk2(ka[0] * EX2(-ba[0]), ka[1] * EX2(-ba[1])); kw.y = pk2(ka[2] * EX2(-ba[2]), ka[3] * EX2(-ba[3]));
;                 kw.z = pk2(kc[0] * EX2(-bb[0]), kc[1] * EX2(-bb[1])); kw.w = pk2(kc[2] * EX2(-bb[2]), kc[3] * EX2(-bb[3]));
;                 const bf16x8 Qd = as_bf16x8(qw), Kd = as_bf16x8(kw);
;                 bf16x4 ke[2]; f32x4 dec[2]; gla_state_ops(ks, Bs, Be, fr, fq, ke, dec);
;                 f32x4 AT = __builtin_amdgcn_mfma_f32_16x16x32_bf16(Kd, Qd, (f32x4){0.f, 0.f, 0.f, 0.f}, 0, 0, 0);
; #pragma unroll
;                 for (int j = 0; j < 4; ++j) { const int pp = fq * 4 + j; const bool keep = dir == 0 ? (pp <= fr) : (pp >= fr); AT[j] = keep ? AT[j] : 0.f; }
;                 u32x2 aw; aw.x = pk2(AT[0], AT[1]); aw.y = pk2(AT[2], AT[3]);
;                 const bf16x4 atb = as_bf16x4(aw);
;                 f32x4 O[4];
; #pragma unroll
;                 for (int db = 0; db < 4; ++db) {
;                     const f32x4 Oa = __builtin_amdgcn_mfma_f32_16x16x16bf16_1k(vt[db], atb, (f32x4){0.f, 0.f, 0.f, 0.f}, 0, 0, 0);
;                     u32x4 sw; sw.x = pk2(S[0][db][0], S[0][db][1]); sw.y = pk2(S[0][db][2], S[0][db][3]); sw.z = pk2(S[1][db][0], S[1][db][1]); sw.w = pk2(S[1][db][2], S[1][db][3]);
;                     const f32x4 Ob = __builtin_amdgcn_mfma_f32_16x16x32_bf16(as_bf16x8(sw), Qd, (f32x4){0.f, 0.f, 0.f, 0.f}, 0, 0, 0);
;                     O[db] = Oa + Ob;
;                 }
; #pragma unroll
;                 for (int kb = 0; kb < 2; ++kb)
; #pragma unroll
.LBB0_834:
	ds_read_b128 v[70:73], v186 offset:4608
	ds_read_b128 v[74:77], v186 offset:4672
	s_waitcnt lgkmcnt(7)
	ds_read_b128 v[66:69], v186
	ds_read_b128 v[78:81], v186 offset:64
	ds_read_b128 v[152:155], v186 offset:2304
	ds_read_b128 v[156:159], v186 offset:2368
	s_waitcnt lgkmcnt(5)
	v_exp_f32_e32 v160, v70
	v_exp_f32_e32 v161, v71
	v_exp_f32_e32 v176, v72
	v_exp_f32_e32 v177, v73
	v_exp_f32_e64 v70, -v70
	v_exp_f32_e64 v71, -v71
	v_exp_f32_e64 v72, -v72
	v_exp_f32_e64 v73, -v73
	s_waitcnt lgkmcnt(3)
	v_pk_mul_f32 v[66:67], v[160:161], v[66:67]
	s_waitcnt lgkmcnt(1)
	v_pk_mul_f32 v[70:71], v[70:71], v[152:153]
	v_exp_f32_e32 v160, v74
	v_pk_mul_f32 v[72:73], v[72:73], v[154:155]
	v_exp_f32_e32 v161, v75
	v_cvt_pk_bf16_f32 v70, v70, v71
	v_cvt_pk_bf16_f32 v71, v72, v73
	v_exp_f32_e64 v72, -v74
	v_exp_f32_e64 v73, -v75
	v_exp_f32_e64 v74, -v76
	v_exp_f32_e64 v75, -v77
	v_pk_mul_f32 v[68:69], v[176:177], v[68:69]
	v_exp_f32_e32 v176, v76
	v_add_u32_e32 v76, 0x1800, v188
	v_exp_f32_e32 v177, v77
	ds_read2_b32 v[152:153], v76 offset0:192 offset1:208
	ds_read2st64_b32 v[76:77], v189 offset0:9 offset1:18
	s_waitcnt lgkmcnt(2)
	v_pk_mul_f32 v[72:73], v[72:73], v[156:157]
	v_pk_mul_f32 v[74:75], v[74:75], v[158:159]
	v_cvt_pk_bf16_f32 v72, v72, v73
	v_cvt_pk_bf16_f32 v73, v74, v75
	v_add_u32_e32 v75, 0x1000, v190
	ds_read2_b32 v[154:155], v75 offset0:144 offset1:164
	v_cvt_pk_bf16_f32 v66, v66, v67
	v_cvt_pk_bf16_f32 v67, v68, v69
	v_pk_mul_f32 v[68:69], v[160:161], v[78:79]
	v_pk_mul_f32 v[78:79], v[176:177], v[80:81]
	v_cvt_pk_bf16_f32 v68, v68, v69
	v_cvt_pk_bf16_f32 v69, v78, v79
	s_waitcnt lgkmcnt(1)
	v_sub_f32_e32 v74, v152, v77
	v_add_u32_e32 v77, 0x800, v190
	ds_read2_b32 v[78:79], v75 offset0:200 offset1:236
	ds_read2_b32 v[160:161], v77 offset0:80 offset1:100
	s_waitcnt lgkmcnt(2)
	v_sub_f32_e32 v75, v152, v155
	v_exp_f32_e32 v74, v74
	v_exp_f32_e32 v75, v75
	ds_read2_b32 v[80:81], v77 offset0:136 offset1:172
	s_waitcnt lgkmcnt(2)
	v_sub_f32_e32 v77, v152, v78
	v_exp_f32_e32 v78, v77
	v_sub_f32_e32 v77, v152, v79
	v_exp_f32_e32 v79, v77
	s_waitcnt lgkmcnt(1)
	v_mov_b32_e32 v77, v161
	v_pk_mul_f32 v[156:157], v[76:77], v[74:75]
	ds_read_b128 v[74:77], v187 offset:6912
	s_waitcnt lgkmcnt(1)
	v_pk_mul_f32 v[78:79], v[80:81], v[78:79]
	v_mfma_f32_16x16x32_bf16 v[70:73], v[70:73], v[66:69], 0
	v_cvt_pk_bf16_f32 v177, v78, v79
	ds_read_b128 v[78:81], v187 offset:6976
	s_waitcnt lgkmcnt(1)
	v_exp_f32_e32 v242, v74
	v_add_u32_e32 v74, 0x1000, v191
	v_exp_f32_e32 v243, v75
	v_exp_f32_e32 v244, v76
	ds_read2_b32 v[74:75], v74 offset0:164 offset1:200
	v_add_u32_e32 v76, 0x800, v191
	ds_read2_b32 v[216:217], v76 offset0:100 offset1:136
	ds_read_b32 v221, v191 offset:2736
	ds_read_b32 v152, v191 offset:5040
	v_sub_f32_e32 v76, v153, v154
	s_waitcnt lgkmcnt(3)
	v_sub_f32_e32 v139, v153, v75
	v_sub_f32_e32 v74, v153, v74
	v_exp_f32_e32 v222, v139
	s_waitcnt lgkmcnt(0)
	v_sub_f32_e32 v139, v153, v152
	v_exp_f32_e32 v218, v76
	v_exp_f32_e32 v219, v74
	v_exp_f32_e32 v223, v139
	v_mov_b32_e32 v161, v216
	v_mov_b32_e32 v220, v217
	v_cndmask_b32_e64 v70, 0, v70, s[58:59]
	v_cndmask_b32_e64 v71, 0, v71, s[60:61]
	v_cndmask_b32_e64 v72, 0, v72, s[62:63]
	v_cndmask_b32_e64 v73, 0, v73, s[64:65]
	v_pk_mul_f32 v[160:161], v[160:161], v[218:219]
	v_pk_mul_f32 v[224:225], v[220:221], v[222:223]
	v_cvt_pk_bf16_f32 v238, v70, v71
	v_cvt_pk_bf16_f32 v239, v72, v73
	v_cvt_pk_bf16_f32 v70, v26, v27
	v_cvt_pk_bf16_f32 v71, v28, v29
	v_cvt_pk_bf16_f32 v72, v42, v43
	v_cvt_pk_bf16_f32 v73, v44, v45
	v_cvt_pk_bf16_f32 v152, v30, v31
	v_cvt_pk_bf16_f32 v153, v32, v33
	v_cvt_pk_bf16_f32 v154, v46, v47
	v_cvt_pk_bf16_f32 v155, v48, v49
	v_cvt_pk_bf16_f32 v216, v34, v35
	v_cvt_pk_bf16_f32 v217, v36, v37
	v_cvt_pk_bf16_f32 v218, v50, v51
	v_cvt_pk_bf16_f32 v219, v52, v53
	v_cvt_pk_bf16_f32 v160, v160, v161
	v_cvt_pk_bf16_f32 v161, v224, v225
	v_cvt_pk_bf16_f32 v224, v38, v39
	v_cvt_pk_bf16_f32 v225, v40, v41
	v_cvt_pk_bf16_f32 v226, v54, v55
	v_cvt_pk_bf16_f32 v227, v56, v57
	v_cvt_pk_bf16_f32 v176, v156, v157
	v_exp_f32_e32 v245, v77
	v_exp_f32_e32 v246, v78
	v_exp_f32_e32 v247, v79
	v_exp_f32_e32 v248, v80
	v_exp_f32_e32 v249, v81
	v_mfma_f32_16x16x16_bf16 v[74:77], v[150:151], v[238:239], 0
	v_mul_f32_e64 v28, v28, v244
	v_mul_f32_e64 v29, v29, v245
	v_pk_mul_f32 v[26:27], v[26:27], v[242:243]
	v_pk_mul_f32 v[32:33], v[32:33], v[244:245]
	v_mfma_f32_16x16x32_bf16 v[70:73], v[70:73], v[66:69], 0
	v_mul_f32_e64 v30, v30, v242
	v_mul_f32_e64 v31, v31, v243
	v_pk_mul_f32 v[36:37], v[36:37], v[244:245]
	v_pk_mul_f32 v[34:35], v[34:35], v[242:243]
	v_mfma_f32_16x16x16_bf16 v[156:159], v[148:149], v[238:239], 0
	v_mul_f32_e64 v40, v40, v244
	v_mul_f32_e64 v41, v41, v245
	v_pk_mul_f32 v[38:39], v[38:39], v[242:243]
	v_pk_mul_f32 v[44:45], v[44:45], v[248:249]
	v_mfma_f32_16x16x32_bf16 v[152:155], v[152:155], v[66:69], 0
	v_mul_f32_e64 v42, v42, v246
	v_mul_f32_e64 v43, v43, v247
	v_pk_mul_f32 v[48:49], v[48:49], v[248:249]
	v_pk_mul_f32 v[46:47], v[46:47], v[246:247]
	v_mfma_f32_16x16x16_bf16 v[220:223], v[146:147], v[238:239], 0
	v_mul_f32_e64 v52, v52, v248
	v_mul_f32_e64 v53, v53, v249
	v_pk_mul_f32 v[50:51], v[50:51], v[246:247]
	v_pk_mul_f32 v[56:57], v[56:57], v[248:249]
	v_mfma_f32_16x16x32_bf16 v[216:219], v[216:219], v[66:69], 0
	v_mul_f32_e64 v54, v54, v246
	v_mul_f32_e64 v55, v55, v247
	s_and_b64 vcc, exec, s[66:67]
	s_mov_b64 s[34:35], -1
	v_mfma_f32_16x16x16_bf16 v[238:241], v[144:145], v[238:239], 0
	v_mfma_f32_16x16x32_bf16 v[224:227], v[224:227], v[66:69], 0
	v_add_f32_e64 v66, v76, v72
	v_add_f32_e64 v67, v77, v73
	v_pk_add_f32 v[68:69], v[74:75], v[70:71]
	v_pk_add_f32 v[70:71], v[158:159], v[154:155]
	v_mfma_f32_16x16x16_bf16 v[26:29], v[176:177], v[150:151], v[26:29]
	v_add_f32_e64 v72, v156, v152
	v_add_f32_e64 v73, v157, v153
	v_pk_add_f32 v[74:75], v[222:223], v[218:219]
	v_pk_add_f32 v[78:79], v[220:221], v[216:217]
	v_mfma_f32_16x16x16_bf16 v[30:33], v[176:177], v[148:149], v[30:33]
	v_add_f32_e64 v76, v240, v226
	v_add_f32_e64 v77, v241, v227
	v_pk_add_f32 v[80:81], v[238:239], v[224:225]
	v_mfma_f32_16x16x16_bf16 v[34:37], v[176:177], v[146:147], v[34:37]
	v_mfma_f32_16x16x16_bf16 v[38:41], v[176:177], v[144:145], v[38:41]
	v_mfma_f32_16x16x16_bf16 v[42:45], v[160:161], v[150:151], v[42:45]
	v_mfma_f32_16x16x16_bf16 v[46:49], v[160:161], v[148:149], v[46:49]
	v_mfma_f32_16x16x16_bf16 v[50:53], v[160:161], v[146:147], v[50:53]
	v_mfma_f32_16x16x16_bf16 v[54:57], v[160:161], v[144:145], v[54:57]
	s_cbranch_vccnz .LBB0_836
; __device__ __forceinline__ void gla_step3(ParamsK p, int l, unsigned char* smem) {
;     ...
;                     float ss = 0.f;
; #pragma unroll
;                     for (int db = 0; db < 4; ++db) { O[db] = O[db] + og[db]; ss += (O[db][0] * O[db][0] + O[db][1] * O[db][1]) + (O[db][2] * O[db][2] + O[db][3] * O[db][3]); }
;                     ss += __shfl_xor(ss, 16); ss += __shfl_xor(ss, 32);
;                     const float rstd = rsqrtf(ss * (1.f / 64.f) + 1e-6f);
; #pragma unroll
;                     for (int db = 0; db < 4; ++db) { const f32x4 n4 = *(const f32x4*)(ngp + db * 16 + fq * 4);
	v_pk_add_f32 v[160:161], v[66:67], v[12:13]
	v_pk_add_f32 v[176:177], v[68:69], v[10:11]
	v_pk_mul_f32 v[144:145], v[160:161], v[160:161]
	v_pk_mul_f32 v[146:147], v[176:177], v[176:177]
	v_pk_add_f32 v[156:157], v[70:71], v[16:17]
	v_pk_mov_b32 v[148:149], v[146:147], v[144:145] op_sel:[1,0]
	v_mov_b32_e32 v147, v145
	v_pk_add_f32 v[158:159], v[72:73], v[14:15]
	v_pk_add_f32 v[144:145], v[148:149], v[146:147]
	v_pk_mul_f32 v[146:147], v[156:157], v[156:157]
	v_pk_mul_f32 v[148:149], v[158:159], v[158:159]
	v_pk_add_f32 v[144:145], v[144:145], v[144:145] op_sel:[0,1] op_sel_hi:[1,0]
	v_pk_mov_b32 v[150:151], v[148:149], v[146:147] op_sel:[1,0]
	v_mov_b32_e32 v149, v147
	v_pk_add_f32 v[148:149], v[150:151], v[148:149]
	v_pk_add_f32 v[150:151], v[80:81], v[22:23]
	v_pk_add_f32 v[148:149], v[148:149], v[148:149] op_sel:[0,1] op_sel_hi:[1,0]
	v_mul_f32_e32 v139, v150, v150
	v_mul_f32_e32 v179, v151, v151
	v_pk_add_f32 v[152:153], v[74:75], v[20:21]
	v_pk_add_f32 v[154:155], v[78:79], v[18:19]
	v_mov_b32_e32 v145, v139
	v_mov_b32_e32 v149, v179
	v_pk_add_f32 v[146:147], v[76:77], v[24:25]
	v_pk_add_f32 v[144:145], v[144:145], v[148:149]
	v_mul_f32_e32 v148, v155, v155
	v_mul_f32_e32 v216, v153, v153
	v_mul_f32_e32 v215, v146, v146
	v_mul_f32_e32 v218, v147, v147
	v_pk_fma_f32 v[148:149], v[154:155], v[154:155], v[148:149] op_sel_hi:[1,1,0]
	v_pk_fma_f32 v[216:217], v[152:153], v[152:153], v[216:217] op_sel_hi:[1,1,0]
	v_mov_b32_e32 v149, v215
	v_mov_b32_e32 v217, v218
	v_pk_add_f32 v[148:149], v[148:149], v[216:217]
	ds_read_b128 v[216:219], v237 offset:8192
	v_pk_add_f32 v[144:145], v[144:145], v[148:149]
	v_and_b32_e32 v179, 0xffff0000, v102
	v_add_f32_e32 v139, v144, v145
	v_xor_b32_e32 v144, 16, v228
	v_cmp_lt_i32_e32 vcc, v144, v143
	s_mov_b64 s[34:35], 0
	s_nop 0
	v_cndmask_b32_e32 v143, v228, v144, vcc
	v_lshlrev_b32_e32 v143, 2, v143
	ds_bpermute_b32 v143, v143, v139
	s_waitcnt lgkmcnt(0)
	v_add_f32_e32 v139, v139, v143
	ds_bpermute_b32 v143, v178, v139
	v_lshlrev_b32_e32 v178, 16, v102
	s_waitcnt lgkmcnt(0)
	v_add_f32_e32 v139, v139, v143
	v_fmamk_f32 v139, v139, 0x3c800000, v162
	v_cmp_gt_f32_e32 vcc, s82, v139
	v_mul_f32_e32 v143, 0x4b800000, v139
	s_nop 0
	v_cndmask_b32_e32 v139, v139, v143, vcc
	v_rsq_f32_e32 v139, v139
	s_nop 0
	v_mul_f32_e32 v143, 0x45800000, v139
	v_cndmask_b32_e32 v148, v139, v143, vcc
	v_mul_f32_e32 v139, 0xbfb8aa3b, v178
	v_exp_f32_e32 v139, v139
	v_pk_mul_f32 v[176:177], v[176:177], v[148:149] op_sel_hi:[1,0]
	v_pk_mul_f32 v[160:161], v[160:161], v[148:149] op_sel_hi:[1,0]
	v_ashrrev_i32_e32 v143, 31, v142
	v_add_f32_e32 v139, 1.0, v139
	v_rcp_f32_e32 v220, v139
	v_mul_f32_e32 v139, 0xbfb8aa3b, v179
	v_exp_f32_e32 v139, v139
	v_lshlrev_b64 v[144:145], 11, v[142:143]
	v_lshl_add_u64 v[144:145], v[110:111], 0, v[144:145]
	v_pk_mul_f32 v[158:159], v[158:159], v[148:149] op_sel_hi:[1,0]
	v_add_f32_e32 v139, 1.0, v139
	v_rcp_f32_e32 v221, v139
	v_pk_mul_f32 v[156:157], v[156:157], v[148:149] op_sel_hi:[1,0]
	v_pk_mul_f32 v[154:155], v[154:155], v[148:149] op_sel_hi:[1,0]
	v_pk_mul_f32 v[152:153], v[152:153], v[148:149] op_sel_hi:[1,0]
	v_pk_mul_f32 v[178:179], v[220:221], v[178:179]
	v_pk_mul_f32 v[150:151], v[150:151], v[148:149] op_sel_hi:[1,0]
	s_waitcnt lgkmcnt(0)
; __device__ __forceinline__ float bflo(unsigned w) { return __uint_as_float(w << 16); }
; __device__ __forceinline__ float bfhi(unsigned w) { return __uint_as_float(w & 0xffff0000u); }
; __device__ __forceinline__ unsigned pk2(float lo, float hi) { return pg8::cvt_pk_bf16(lo, hi); }
; __device__ __forceinline__ float silu_f(float v) { return v * __builtin_amdgcn_rcpf(1.f + __expf(-v)); }
; __device__ __forceinline__ void gla_step3(ParamsK p, int l, unsigned char* smem) {
;     ...
; #pragma unroll
;                     for (int db = 0; db < 4; ++db) { const f32x4 n4 = *(const f32x4*)(ngp + db * 16 + fq * 4);
;                         const float r0 = bflo(rgw[db].x), r1 = bfhi(rgw[db].x), r2 = bflo(rgw[db].y), r3 = bfhi(rgw[db].y);
;                         u32x2 w; w.x = pk2(O[db][0] * rstd * n4[0] * silu_f(r0), O[db][1] * rstd * n4[1] * silu_f(r1));
;                         w.y = pk2(O[db][2] * rstd * n4[2] * silu_f(r2), O[db][3] * rstd * n4[3] * silu_f(r3));
;                         *(u32x2*)(MIX + (size_t)row * DM + h * 64 + db * 16 + fq * 4) = w; }
	v_pk_mul_f32 v[176:177], v[216:217], v[176:177]
	s_nop 0
	v_pk_mul_f32 v[176:177], v[178:179], v[176:177]
	v_lshlrev_b32_e32 v178, 16, v103
	v_mul_f32_e32 v139, 0xbfb8aa3b, v178
	v_exp_f32_e32 v139, v139
	v_and_b32_e32 v179, 0xffff0000, v103
	v_pk_mul_f32 v[160:161], v[218:219], v[160:161]
	v_cvt_pk_bf16_f32 v176, v176, v177
	v_add_f32_e32 v139, 1.0, v139
	v_rcp_f32_e32 v216, v139
	v_mul_f32_e32 v139, 0xbfb8aa3b, v179
	v_exp_f32_e32 v139, v139
	s_nop 0
	v_add_f32_e32 v139, 1.0, v139
	v_rcp_f32_e32 v217, v139
	s_nop 0
	v_pk_mul_f32 v[178:179], v[216:217], v[178:179]
	s_nop 0
	v_pk_mul_f32 v[160:161], v[178:179], v[160:161]
	s_nop 0
	v_cvt_pk_bf16_f32 v177, v160, v161
	global_store_dwordx2 v[144:145], v[176:177], off
	ds_read_b128 v[176:179], v237 offset:8256
	v_lshlrev_b32_e32 v160, 16, v100
	v_mul_f32_e32 v139, 0xbfb8aa3b, v160
	v_exp_f32_e32 v139, v139
	v_and_b32_e32 v161, 0xffff0000, v100
	v_add_f32_e32 v139, 1.0, v139
	v_rcp_f32_e32 v216, v139
	v_mul_f32_e32 v139, 0xbfb8aa3b, v161
	v_exp_f32_e32 v139, v139
	s_waitcnt lgkmcnt(0)
	v_pk_mul_f32 v[158:159], v[176:177], v[158:159]
	v_add_f32_e32 v139, 1.0, v139
	v_rcp_f32_e32 v217, v139
	v_pk_mul_f32 v[156:157], v[178:179], v[156:157]
	v_pk_mul_f32 v[160:161], v[216:217], v[160:161]
	s_nop 0
	v_pk_mul_f32 v[158:159], v[160:161], v[158:159]
	v_lshlrev_b32_e32 v160, 16, v101
	v_mul_f32_e32 v139, 0xbfb8aa3b, v160
	v_exp_f32_e32 v139, v139
	v_and_b32_e32 v161, 0xffff0000, v101
	v_cvt_pk_bf16_f32 v158, v158, v159
	v_add_f32_e32 v139, 1.0, v139
	v_rcp_f32_e32 v176, v139
	v_mul_f32_e32 v139, 0xbfb8aa3b, v161
	v_exp_f32_e32 v139, v139
	s_nop 0
	v_add_f32_e32 v139, 1.0, v139
	v_rcp_f32_e32 v177, v139
	s_nop 0
	v_pk_mul_f32 v[160:161], v[176:177], v[160:161]
	s_nop 0
	v_pk_mul_f32 v[156:157], v[160:161], v[156:157]
	v_lshlrev_b32_e32 v160, 16, v98
	v_cvt_pk_bf16_f32 v159, v156, v157
	global_store_dwordx2 v[144:145], v[158:159], off offset:32
	ds_read_b128 v[156:159], v237 offset:8320
	v_mul_f32_e32 v139, 0xbfb8aa3b, v160
	v_exp_f32_e32 v139, v139
	v_and_b32_e32 v161, 0xffff0000, v98
	v_add_f32_e32 v139, 1.0, v139
	v_rcp_f32_e32 v176, v139
	v_mul_f32_e32 v139, 0xbfb8aa3b, v161
	v_exp_f32_e32 v139, v139
	s_waitcnt lgkmcnt(0)
	v_pk_mul_f32 v[154:155], v[156:157], v[154:155]
	v_add_f32_e32 v139, 1.0, v139
	v_rcp_f32_e32 v177, v139
	v_pk_mul_f32 v[152:153], v[158:159], v[152:153]
	v_lshlrev_b32_e32 v158, 16, v104
	v_mul_f32_e32 v143, 0xbfb8aa3b, v158
	v_pk_mul_f32 v[156:157], v[176:177], v[160:161]
	v_exp_f32_e32 v143, v143
	v_pk_mul_f32 v[154:155], v[156:157], v[154:155]
	v_lshlrev_b32_e32 v156, 16, v99
	v_mul_f32_e32 v139, 0xbfb8aa3b, v156
	v_exp_f32_e32 v139, v139
	v_and_b32_e32 v157, 0xffff0000, v99
	v_cvt_pk_bf16_f32 v154, v154, v155
	v_and_b32_e32 v159, 0xffff0000, v104
	v_add_f32_e32 v139, 1.0, v139
	v_rcp_f32_e32 v160, v139
	v_mul_f32_e32 v139, 0xbfb8aa3b, v157
	v_exp_f32_e32 v139, v139
	v_add_f32_e32 v143, 1.0, v143
	v_add_f32_e32 v139, 1.0, v139
	v_rcp_f32_e32 v161, v139
	v_lshlrev_b32_e32 v139, 16, v105
	v_pk_mul_f32 v[156:157], v[160:161], v[156:157]
	s_nop 0
	v_pk_mul_f32 v[152:153], v[156:157], v[152:153]
	v_rcp_f32_e32 v160, v143
	v_cvt_pk_bf16_f32 v155, v152, v153
	global_store_dwordx2 v[144:145], v[154:155], off offset:64
	ds_read_b128 v[152:155], v237 offset:8384
	v_mul_f32_e32 v143, 0xbfb8aa3b, v159
	v_exp_f32_e32 v143, v143
	v_and_b32_e32 v156, 0xffff0000, v105
	v_mul_f32_e32 v157, v147, v148
	v_add_f32_e32 v143, 1.0, v143
	v_rcp_f32_e32 v161, v143
	v_mul_f32_e32 v143, v146, v148
	s_waitcnt lgkmcnt(0)
	v_mul_f32_e32 v146, v154, v143
	v_mul_f32_e32 v143, 0xbfb8aa3b, v139
	v_exp_f32_e32 v143, v143
	v_pk_mul_f32 v[150:151], v[152:153], v[150:151]
	v_pk_mul_f32 v[152:153], v[160:161], v[158:159]
	v_add_f32_e32 v143, 1.0, v143
	v_rcp_f32_e32 v143, v143
	v_pk_mul_f32 v[150:151], v[152:153], v[150:151]
	v_mul_f32_e32 v152, v143, v139
	v_mul_f32_e32 v139, 0xbfb8aa3b, v156
	v_exp_f32_e32 v139, v139
	v_cvt_pk_bf16_f32 v150, v150, v151
	v_add_f32_e32 v139, 1.0, v139
	v_rcp_f32_e32 v154, v139
	s_nop 0
	v_pk_mul_f32 v[148:149], v[154:155], v[156:157]
	s_nop 0
	v_mov_b32_e32 v153, v148
	v_mov_b32_e32 v147, v149
	v_pk_mul_f32 v[146:147], v[152:153], v[146:147]

; __global__ void __launch_bounds__(512, 2) fwd_megakernel(Params p_unused) {
;     extern __shared__ __attribute__((aligned(16))) unsigned char smem[];
;     cg::grid_group grid = cg::this_grid();
	.amdhsa_kernel _Z14fwd_megakernel6Params
		.amdhsa_group_segment_fixed_size 16
		.amdhsa_private_segment_fixed_size 0
		.amdhsa_kernarg_size 456
		.amdhsa_user_sgpr_count 2
		.amdhsa_user_sgpr_dispatch_ptr 0
		.amdhsa_user_sgpr_queue_ptr 0
		.amdhsa_user_sgpr_kernarg_segment_ptr 1
		.amdhsa_user_sgpr_dispatch_id 0
		.amdhsa_user_sgpr_kernarg_preload_length 0
		.amdhsa_user_sgpr_kernarg_preload_offset 0
		.amdhsa_user_sgpr_private_segment_size 0
		.amdhsa_uses_dynamic_stack 0
		.amdhsa_enable_private_segment 0
		.amdhsa_system_sgpr_workgroup_id_x 1
		.amdhsa_system_sgpr_workgroup_id_y 0
		.amdhsa_system_sgpr_workgroup_id_z 0
		.amdhsa_system_sgpr_workgroup_info 0
		.amdhsa_system_vgpr_workitem_id 2
		.amdhsa_next_free_vgpr 256
		.amdhsa_next_free_sgpr 102
		.amdhsa_accum_offset 256
		.amdhsa_reserve_vcc 1
		.amdhsa_float_round_mode_32 0
		.amdhsa_float_round_mode_16_64 0
		.amdhsa_float_denorm_mode_32 3
		.amdhsa_float_denorm_mode_16_64 3
		.amdhsa_dx10_clamp 1
		.amdhsa_ieee_mode 1
		.amdhsa_fp16_overflow 0
		.amdhsa_tg_split 0
		.amdhsa_exception_fp_ieee_invalid_op 0
		.amdhsa_exception_fp_denorm_src 0
		.amdhsa_exception_fp_ieee_div_zero 0
		.amdhsa_exception_fp_ieee_overflow 0
		.amdhsa_exception_fp_ieee_underflow 0
		.amdhsa_exception_fp_ieee_inexact 0
		.amdhsa_exception_int_div_zero 0
	.end_amdhsa_kernel

; __global__ void __launch_bounds__(512, 2) fwd_megakernel(Params p_unused) {
;     extern __shared__ __attribute__((aligned(16))) unsigned char smem[];
;     cg::grid_group grid = cg::this_grid();
amdhsa.kernels:
  - .agpr_count:     0
    .args:
      - .offset:         0
        .size:           200
        .value_kind:     by_value
      - .offset:         200
        .size:           4
        .value_kind:     hidden_block_count_x
      - .offset:         204
        .size:           4
        .value_kind:     hidden_block_count_y
      - .offset:         208
        .size:           4
        .value_kind:     hidden_block_count_z
      - .offset:         212
        .size:           2
        .value_kind:     hidden_group_size_x
      - .offset:         214
        .size:           2
        .value_kind:     hidden_group_size_y
      - .offset:         216
        .size:           2
        .value_kind:     hidden_group_size_z
      - .offset:         218
        .size:           2
        .value_kind:     hidden_remainder_x
      - .offset:         220
        .size:           2
        .value_kind:     hidden_remainder_y
      - .offset:         222
        .size:           2
        .value_kind:     hidden_remainder_z
      - .offset:         240
        .size:           8
        .value_kind:     hidden_global_offset_x
      - .offset:         248
        .size:           8
        .value_kind:     hidden_global_offset_y
      - .offset:         256
        .size:           8
        .value_kind:     hidden_global_offset_z
      - .offset:         264
        .size:           2
        .value_kind:     hidden_grid_dims
      - .offset:         288
        .size:           8
        .value_kind:     hidden_multigrid_sync_arg
      - .offset:         320
        .size:           4
        .value_kind:     hidden_dynamic_lds_size
    .group_segment_fixed_size: 16
    .kernarg_segment_align: 8
    .kernarg_segment_size: 456
    .language:       OpenCL C
    .language_version:
      - 2
      - 0
    .max_flat_workgroup_size: 512
    .name:           _Z14fwd_megakernel6Params
    .private_segment_fixed_size: 0
    .sgpr_count:     108
    .sgpr_spill_count: 178
    .symbol:         _Z14fwd_megakernel6Params.kd
    .uniform_work_group_size: 1
    .uses_dynamic_stack: false
    .vgpr_count:     256
    .vgpr_spill_count: 0
    .wavefront_size: 64
